# attention: next item's K-rope table rows requested at the end of q-tile 1 (before its output stores); first item in the prologue; staging waits K=vmcnt(20), tables=vmcnt(12)
# baseline (speedup 1.0000x reference)
.LBB0_345:
	s_or_b64 exec, exec, s[2:3]
	s_add_u32 s82, s84, 0x80000
	s_addc_u32 s83, s85, 0
	s_add_u32 s92, s84, 0xc0000
	s_addc_u32 s93, s85, 0
	s_lshl_b32 s58, s97, 5
	s_and_b32 s58, s58, 0x780
	s_addk_i32 s58, 0xff80
	v_add_u32_e32 v230, s58, v250
	v_lshl_add_u32 v230, v230, 7, v248
	v_max_i32_e32 v231, v248, v230
	global_load_dwordx4 v[116:119], v231, s[82:83]
	global_load_dwordx4 v[154:157], v231, s[92:93]
	v_add_u32_e32 v230, 0x400, v230
	v_max_i32_e32 v231, v248, v230
	global_load_dwordx4 v[44:47], v231, s[82:83]
	global_load_dwordx4 v[68:71], v231, s[92:93]
	v_add_u32_e32 v230, 0x400, v230
	v_max_i32_e32 v231, v248, v230
	global_load_dwordx4 v[158:161], v231, s[82:83]
	global_load_dwordx4 v[162:165], v231, s[92:93]
	v_add_u32_e32 v230, 0x400, v230
	v_max_i32_e32 v231, v248, v230
	global_load_dwordx4 v[40:43], v231, s[82:83]
	global_load_dwordx4 v[48:51], v231, s[92:93]
	s_waitcnt vmcnt(0)
	ds_write_b128 v33, v[16:19]
	ds_write_b128 v33, v[20:23] offset:1024
	ds_write_b128 v35, v[24:27]
	ds_write_b128 v35, v[28:31] offset:1024
	ds_write_b32 v10, v11
	ds_write_b32 v10, v12 offset:256
	s_waitcnt lgkmcnt(0)
	v_mbcnt_lo_u32_b32 v0, -1, 0
	v_mbcnt_hi_u32_b32 v4, -1, v0
	v_and_b32_e32 v1, 64, v4
	v_xor_b32_e32 v0, 1, v4
	v_add_u32_e32 v5, 64, v1
	v_bfe_u32 v3, v251, 5, 1
	v_cmp_lt_i32_e32 vcc, v0, v5
	v_xor_b32_e32 v10, 32, v4
	v_and_b32_e32 v184, 31, v251
	v_cndmask_b32_e32 v0, v4, v0, vcc
	v_cmp_lt_i32_e32 vcc, v10, v5
	v_lshlrev_b32_e32 v5, 2, v3
	v_or_b32_e32 v16, 2, v5
	v_cmp_gt_u32_e64 s[6:7], v16, v184
	v_or_b32_e32 v16, 3, v5
	s_add_u32 s82, s84, 0x80000
	v_cmp_gt_u32_e64 s[8:9], v16, v184
	v_or_b32_e32 v16, 8, v5
	s_addc_u32 s83, s85, 0
	v_cmp_gt_u32_e64 s[10:11], v16, v184
	v_or_b32_e32 v16, 9, v5
	s_add_u32 s92, s84, 0xc0000
	v_cmp_gt_u32_e64 s[12:13], v16, v184
	v_or_b32_e32 v16, 10, v5
	s_addc_u32 s93, s85, 0
	s_lshr_b32 s1, s0, 7
	s_and_b32 s91, s0, 64
	s_movk_i32 s0, 0x90
	v_cmp_gt_u32_e64 s[14:15], v16, v184
	v_or_b32_e32 v16, 11, v5
	v_mad_u32_u24 v6, v182, s0, 0
	s_movk_i32 s0, 0x208
	v_cmp_gt_u32_e64 s[16:17], v16, v184
	v_or_b32_e32 v16, 16, v5
	v_lshlrev_b32_e32 v96, 4, v3
	v_mad_u32_u24 v9, v120, s0, 0
	v_cndmask_b32_e32 v4, v4, v10, vcc
	s_lshr_b32 s0, s91, 5
	v_cmp_gt_u32_e64 s[18:19], v16, v184
	v_or_b32_e32 v16, 17, v5
	v_writelane_b32 v255, s1, 14
	v_lshlrev_b32_e32 v126, 3, v3
	v_lshlrev_b32_e32 v188, 2, v4
	v_add_u32_e32 v4, 0, v96
	s_or_b32 s1, s0, 1
	s_add_i32 s33, s0, 2
	s_add_i32 s54, s0, 3
	s_or_b32 s0, s0, 4
	v_cmp_gt_u32_e64 s[20:21], v16, v184
	v_or_b32_e32 v16, 18, v5
	v_sub_u32_e32 v10, v4, v126
	v_cmp_gt_u32_e64 s[22:23], v16, v184
	v_or_b32_e32 v16, 19, v5
	s_cmp_eq_u32 s91, 0
	v_readlane_b32 s2, v255, 6
	v_lshl_or_b32 v15, s0, 5, v184
	v_cmp_gt_u32_e64 s[24:25], v16, v184
	v_or_b32_e32 v16, 24, v5
	s_cselect_b64 s[36:37], -1, 0
	v_lshl_add_u32 v20, s0, 6, v10
	s_or_b32 s0, s91, 32
	v_mov_b32_e32 v127, v97
	v_readlane_b32 s3, v255, 7
	v_lshl_or_b32 v12, s1, 5, v184
	v_cmp_gt_u32_e64 s[26:27], v16, v184
	v_or_b32_e32 v16, 25, v5
	v_lshl_add_u32 v17, s1, 6, v10
	s_lshr_b32 s1, s0, 5
	v_lshl_add_u64 v[146:147], s[2:3], 0, v[126:127]
	v_lshl_or_b32 v13, s33, 5, v184
	v_lshl_or_b32 v14, s54, 5, v184
	v_cmp_gt_u32_e64 s[2:3], v5, v184
	v_cmp_lt_u32_e64 s[4:5], v5, v184
	v_cmp_gt_u32_e64 s[28:29], v16, v184
	v_or_b32_e32 v16, 26, v5
	v_or_b32_e32 v5, 27, v5
	v_lshl_add_u32 v18, s33, 6, v10
	v_lshl_add_u32 v19, s54, 6, v10
	s_add_i32 s33, s1, 1
	s_add_i32 s54, s1, 2
	s_add_i32 s55, s1, 3
	s_or_b32 s1, s1, 4
	v_writelane_b32 v255, s0, 15
	v_and_b32_e32 v2, 1, v251
	v_cmp_gt_u32_e64 s[34:35], v5, v184
	v_lshl_add_u32 v5, s91, 1, v10
	v_or_b32_e32 v21, s0, v184
	v_lshl_or_b32 v25, s1, 5, v184
	v_lshl_add_u32 v26, s0, 1, v10
	v_lshl_add_u32 v27, s33, 6, v10
	v_lshl_add_u32 v28, s54, 6, v10
	v_lshl_add_u32 v29, s55, 6, v10
	v_lshl_add_u32 v10, s1, 6, v10
	v_readlane_b32 s0, v255, 1
	v_or_b32_e32 v185, s91, v184
	v_lshlrev_b32_e32 v187, 2, v0
	v_lshlrev_b32_e32 v0, 6, v2
	v_lshlrev_b32_e32 v7, 5, v2
	v_lshlrev_b32_e32 v2, 4, v251
	v_lshl_or_b32 v22, s33, 5, v184
	v_lshl_or_b32 v23, s54, 5, v184
	v_lshl_or_b32 v24, s55, 5, v184
	v_readlane_b32 s1, v255, 2
	v_mov_b32_e32 v1, v97
	v_and_b32_e32 v8, 0x3fc, v251
	v_and_b32_e32 v2, 16, v2
	v_mul_u32_u24_e32 v11, 0x90, v185
	v_mul_u32_u24_e32 v12, 0x90, v12
	v_mul_u32_u24_e32 v13, 0x90, v13
	v_mul_u32_u24_e32 v14, 0x90, v14
	v_mul_u32_u24_e32 v15, 0x90, v15
	v_cmp_gt_u32_e64 s[30:31], v16, v184
	v_mul_u32_u24_e32 v16, 0x208, v184
	v_mul_u32_u24_e32 v21, 0x90, v21
	v_mul_u32_u24_e32 v22, 0x90, v22
	v_mul_u32_u24_e32 v23, 0x90, v23
	v_mul_u32_u24_e32 v24, 0x90, v24
	v_mul_u32_u24_e32 v25, 0x90, v25
	v_lshlrev_b32_e32 v96, 5, v3
	s_lshl_b32 s1, s0, 5
	s_lshl_b32 s0, s0, 2
	v_add_u32_e32 v186, 0xffffff80, v182
	s_mov_b32 s95, 0
	v_lshl_add_u64 v[142:143], s[82:83], 0, v[0:1]
	v_lshl_add_u64 v[144:145], s[92:93], 0, v[0:1]
	v_or_b32_e32 v127, 16, v126
	v_lshl_add_u64 v[148:149], s[78:79], 0, v[0:1]
	v_lshl_add_u64 v[150:151], s[76:77], 0, v[96:97]
	v_mov_b32_e32 v242, 0
	v_add_u32_e32 v242, 0x1b000, v242
	v_add_u32_e32 v243, v242, v96
	v_add_u32_e32 v243, 0x100, v243
	v_add_u32_e32 v242, v242, v0
	s_lshl_b32 s90, s97, 2
	v_writelane_b32 v255, s0, 16
	s_movk_i32 s65, 0xc00
	s_mov_b32 s54, 0xffff0000
	v_mov_b32_e32 v189, 0x358637bd
	v_add_u32_e32 v190, v6, v7
	v_add_u32_e32 v191, v9, v8
	v_lshlrev_b32_e32 v152, 1, v2
	v_add_u32_e32 v192, v4, v11
	v_add_u32_e32 v193, v4, v12
	v_add_u32_e32 v194, v4, v13
	v_add_u32_e32 v195, v4, v14
	v_add_u32_e32 v196, v4, v15
	v_add_u32_e32 v197, v5, v16
	v_add_u32_e32 v198, v17, v16
	v_add_u32_e32 v199, v18, v16
	v_add_u32_e32 v200, v19, v16
	v_add_u32_e32 v201, v20, v16
	v_add_u32_e32 v202, v4, v21
	v_add_u32_e32 v203, v4, v22
	v_add_u32_e32 v204, v4, v23
	v_add_u32_e32 v205, v4, v24
	v_add_u32_e32 v206, v4, v25
	v_add_u32_e32 v207, v26, v16
	v_add_u32_e32 v208, v27, v16
	v_add_u32_e32 v209, v28, v16
	v_add_u32_e32 v210, v29, v16
	v_add_u32_e32 v211, v10, v16
	v_mov_b32_e32 v212, 0xff800000
	s_mov_b32 s33, s97
	s_branch .LBB0_348

.LBB0_347:
	v_cndmask_b32_e64 v72, v48, v212, s[2:3]
	v_cndmask_b32_e64 v167, v72, v48, s[4:5]
	v_max3_f32 v48, v98, s64, v105
	v_max3_f32 v48, v48, v104, v103
	v_max3_f32 v48, v48, v102, v101
	v_max3_f32 v48, v48, v100, v99
	v_max3_f32 v48, v48, v71, v70
	v_max3_f32 v48, v48, v69, v68
	v_max3_f32 v48, v48, v67, v66
	v_max3_f32 v48, v48, v65, v64
	v_max3_f32 v48, v48, v32, v33
	v_max3_f32 v48, v48, v34, v35
	v_max3_f32 v48, v48, v36, v37
	v_max3_f32 v48, v48, v38, v39
	v_max3_f32 v48, v48, v40, v41
	v_max3_f32 v48, v48, v42, v43
	v_max3_f32 v48, v48, v44, v45
	v_max3_f32 v48, v48, v46, v47
	v_max3_f32 v48, v48, v16, v17
	v_max3_f32 v48, v48, v18, v19
	v_max3_f32 v48, v48, v20, v21
	v_max3_f32 v48, v48, v22, v23
	v_max3_f32 v48, v48, v24, v25
	v_max3_f32 v48, v48, v26, v27
	v_max3_f32 v48, v48, v28, v29
	v_max3_f32 v48, v48, v30, v31
	v_max3_f32 v48, v48, v0, v1
	v_max3_f32 v48, v48, v2, v3
	v_max3_f32 v48, v48, v4, v5
	v_max3_f32 v48, v48, v6, v7
	v_max3_f32 v48, v48, v8, v9
	v_max3_f32 v48, v48, v10, v11
	v_max3_f32 v48, v48, v12, v13
	v_cndmask_b32_e64 v166, v212, v49, s[4:5]
	v_max3_f32 v48, v48, v14, v15
	v_cndmask_b32_e64 v168, v50, v212, s[6:7]
	v_cndmask_b32_e64 v169, v51, v212, s[8:9]
	v_max3_f32 v48, v48, v167, v166
	v_cndmask_b32_e64 v170, v52, v212, s[10:11]
	v_cndmask_b32_e64 v171, v53, v212, s[12:13]
	v_max3_f32 v48, v48, v168, v169
	v_cndmask_b32_e64 v172, v54, v212, s[14:15]
	v_cndmask_b32_e64 v173, v55, v212, s[16:17]
	v_max3_f32 v48, v48, v170, v171
	v_cndmask_b32_e64 v174, v56, v212, s[18:19]
	v_cndmask_b32_e64 v175, v57, v212, s[20:21]
	v_max3_f32 v48, v48, v172, v173
	v_cndmask_b32_e64 v176, v58, v212, s[22:23]
	v_cndmask_b32_e64 v177, v59, v212, s[24:25]
	v_max3_f32 v48, v48, v174, v175
	v_cndmask_b32_e64 v178, v60, v212, s[26:27]
	v_cndmask_b32_e64 v179, v61, v212, s[28:29]
	v_max3_f32 v48, v48, v176, v177
	v_cndmask_b32_e64 v180, v62, v212, s[30:31]
	v_cndmask_b32_e64 v181, v63, v212, s[34:35]
	v_max3_f32 v48, v48, v178, v179
	v_max3_f32 v48, v48, v180, v181
	ds_bpermute_b32 v49, v188, v48
	v_or_b32_e32 v153, s89, v118
	v_readlane_b32 s0, v255, 16
	s_add_i32 s96, s96, s1
	s_add_i32 s90, s90, s0
	s_waitcnt lgkmcnt(0)
	v_max3_f32 v213, v48, v49, v96
	v_sub_f32_e32 v50, v104, v213
	v_exp_f32_e32 v154, v50
	v_sub_f32_e32 v50, v103, v213
	v_exp_f32_e32 v155, v50
	v_sub_f32_e32 v50, v102, v213
	v_exp_f32_e32 v160, v50
	v_sub_f32_e32 v50, v101, v213
	v_exp_f32_e32 v161, v50
	v_sub_f32_e32 v50, v100, v213
	v_sub_f32_e32 v48, v98, v213
	v_exp_f32_e32 v164, v50
	v_sub_f32_e32 v50, v99, v213
	v_exp_f32_e32 v110, v48
	v_sub_f32_e32 v48, v105, v213
	v_exp_f32_e32 v165, v50
	v_sub_f32_e32 v50, v71, v213
	v_exp_f32_e32 v111, v48
	v_exp_f32_e32 v102, v50
	v_sub_f32_e32 v50, v70, v213
	v_exp_f32_e32 v103, v50
	v_pk_add_f32 v[232:233], v[68:69], v[212:213] op_sel:[0,1] op_sel_hi:[1,1] neg_lo:[0,1] neg_hi:[0,1]
	v_pk_add_f32 v[234:235], v[34:35], v[212:213] op_sel:[0,1] op_sel_hi:[1,1] neg_lo:[0,1] neg_hi:[0,1]
	v_exp_f32_e32 v112, v233
	v_exp_f32_e32 v106, v234
	v_exp_f32_e32 v113, v232
	v_pk_add_f32 v[232:233], v[66:67], v[212:213] op_sel:[0,1] op_sel_hi:[1,1] neg_lo:[0,1] neg_hi:[0,1]
	v_exp_f32_e32 v107, v235
	v_pk_add_f32 v[234:235], v[36:37], v[212:213] op_sel:[0,1] op_sel_hi:[1,1] neg_lo:[0,1] neg_hi:[0,1]
	v_pk_add_f32 v[48:49], v[110:111], 0 op_sel_hi:[1,0]
	v_exp_f32_e32 v156, v233
	v_exp_f32_e32 v118, v234
	v_pk_add_f32 v[48:49], v[154:155], v[48:49]
	v_exp_f32_e32 v157, v232
	v_pk_add_f32 v[232:233], v[64:65], v[212:213] op_sel:[0,1] op_sel_hi:[1,1] neg_lo:[0,1] neg_hi:[0,1]
	v_exp_f32_e32 v119, v235
	v_pk_add_f32 v[234:235], v[38:39], v[212:213] op_sel:[0,1] op_sel_hi:[1,1] neg_lo:[0,1] neg_hi:[0,1]
	v_pk_add_f32 v[48:49], v[160:161], v[48:49]
	v_exp_f32_e32 v162, v233
	v_pk_add_f32 v[236:237], v[32:33], v[212:213] op_sel:[0,1] op_sel_hi:[1,1] neg_lo:[0,1] neg_hi:[0,1]
	v_exp_f32_e32 v158, v234
	v_pk_add_f32 v[48:49], v[164:165], v[48:49]
	v_exp_f32_e32 v163, v232
	v_exp_f32_e32 v78, v236
	v_exp_f32_e32 v159, v235
	v_pk_add_f32 v[232:233], v[40:41], v[212:213] op_sel:[0,1] op_sel_hi:[1,1] neg_lo:[0,1] neg_hi:[0,1]
	v_pk_add_f32 v[48:49], v[102:103], v[48:49]
	v_exp_f32_e32 v79, v237
	v_exp_f32_e32 v68, v232
	v_pk_add_f32 v[48:49], v[112:113], v[48:49]
	v_exp_f32_e32 v69, v233
	v_pk_add_f32 v[232:233], v[42:43], v[212:213] op_sel:[0,1] op_sel_hi:[1,1] neg_lo:[0,1] neg_hi:[0,1]
	v_pk_add_f32 v[234:235], v[18:19], v[212:213] op_sel:[0,1] op_sel_hi:[1,1] neg_lo:[0,1] neg_hi:[0,1]
	v_pk_add_f32 v[236:237], v[2:3], v[212:213] op_sel:[0,1] op_sel_hi:[1,1] neg_lo:[0,1] neg_hi:[0,1]
	v_pk_add_f32 v[48:49], v[156:157], v[48:49]
	v_exp_f32_e32 v76, v232
	v_exp_f32_e32 v72, v234
	v_exp_f32_e32 v60, v236
	v_pk_add_f32 v[48:49], v[162:163], v[48:49]
	v_exp_f32_e32 v77, v233
	v_pk_add_f32 v[232:233], v[44:45], v[212:213] op_sel:[0,1] op_sel_hi:[1,1] neg_lo:[0,1] neg_hi:[0,1]
	v_exp_f32_e32 v73, v235
	v_pk_add_f32 v[234:235], v[20:21], v[212:213] op_sel:[0,1] op_sel_hi:[1,1] neg_lo:[0,1] neg_hi:[0,1]
	v_exp_f32_e32 v61, v237
	v_pk_add_f32 v[236:237], v[4:5], v[212:213] op_sel:[0,1] op_sel_hi:[1,1] neg_lo:[0,1] neg_hi:[0,1]
	v_pk_add_f32 v[32:33], v[78:79], v[48:49]
	v_exp_f32_e32 v104, v232
	v_exp_f32_e32 v100, v234
	v_exp_f32_e32 v66, v236
	v_pk_add_f32 v[32:33], v[106:107], v[32:33]
	v_exp_f32_e32 v105, v233
	v_pk_add_f32 v[232:233], v[46:47], v[212:213] op_sel:[0,1] op_sel_hi:[1,1] neg_lo:[0,1] neg_hi:[0,1]
	v_exp_f32_e32 v101, v235
	v_pk_add_f32 v[234:235], v[22:23], v[212:213] op_sel:[0,1] op_sel_hi:[1,1] neg_lo:[0,1] neg_hi:[0,1]
	v_exp_f32_e32 v67, v237
	v_pk_add_f32 v[236:237], v[6:7], v[212:213] op_sel:[0,1] op_sel_hi:[1,1] neg_lo:[0,1] neg_hi:[0,1]
	v_pk_add_f32 v[32:33], v[118:119], v[32:33]
	v_exp_f32_e32 v114, v232
	v_pk_add_f32 v[238:239], v[16:17], v[212:213] op_sel:[0,1] op_sel_hi:[1,1] neg_lo:[0,1] neg_hi:[0,1]
	v_exp_f32_e32 v108, v234
	v_exp_f32_e32 v74, v236
	v_pk_add_f32 v[32:33], v[158:159], v[32:33]
	v_exp_f32_e32 v115, v233
	v_exp_f32_e32 v64, v238
	v_exp_f32_e32 v109, v235
	v_pk_add_f32 v[232:233], v[24:25], v[212:213] op_sel:[0,1] op_sel_hi:[1,1] neg_lo:[0,1] neg_hi:[0,1]
	v_exp_f32_e32 v75, v237
	v_pk_add_f32 v[234:235], v[8:9], v[212:213] op_sel:[0,1] op_sel_hi:[1,1] neg_lo:[0,1] neg_hi:[0,1]
	v_pk_add_f32 v[32:33], v[68:69], v[32:33]
	v_exp_f32_e32 v65, v239
	v_exp_f32_e32 v58, v232
	v_exp_f32_e32 v48, v234
	v_pk_add_f32 v[32:33], v[76:77], v[32:33]
	v_exp_f32_e32 v59, v233
	v_pk_add_f32 v[232:233], v[26:27], v[212:213] op_sel:[0,1] op_sel_hi:[1,1] neg_lo:[0,1] neg_hi:[0,1]
	v_exp_f32_e32 v49, v235
	v_pk_add_f32 v[234:235], v[10:11], v[212:213] op_sel:[0,1] op_sel_hi:[1,1] neg_lo:[0,1] neg_hi:[0,1]
	v_pk_add_f32 v[32:33], v[104:105], v[32:33]
	v_exp_f32_e32 v62, v232
	v_exp_f32_e32 v50, v234
	v_pk_add_f32 v[32:33], v[114:115], v[32:33]
	v_exp_f32_e32 v63, v233
	v_pk_add_f32 v[232:233], v[28:29], v[212:213] op_sel:[0,1] op_sel_hi:[1,1] neg_lo:[0,1] neg_hi:[0,1]
	v_exp_f32_e32 v51, v235
	v_pk_add_f32 v[234:235], v[12:13], v[212:213] op_sel:[0,1] op_sel_hi:[1,1] neg_lo:[0,1] neg_hi:[0,1]
	v_pk_add_f32 v[16:17], v[64:65], v[32:33]
	v_exp_f32_e32 v70, v232
	v_exp_f32_e32 v52, v234
	v_pk_add_f32 v[16:17], v[72:73], v[16:17]
	v_exp_f32_e32 v71, v233
	v_pk_add_f32 v[232:233], v[30:31], v[212:213] op_sel:[0,1] op_sel_hi:[1,1] neg_lo:[0,1] neg_hi:[0,1]
	v_exp_f32_e32 v53, v235
	v_pk_add_f32 v[234:235], v[14:15], v[212:213] op_sel:[0,1] op_sel_hi:[1,1] neg_lo:[0,1] neg_hi:[0,1]
	v_pk_add_f32 v[16:17], v[100:101], v[16:17]
	v_exp_f32_e32 v98, v232
	v_pk_add_f32 v[236:237], v[0:1], v[212:213] op_sel:[0,1] op_sel_hi:[1,1] neg_lo:[0,1] neg_hi:[0,1]
	v_exp_f32_e32 v54, v234
	v_pk_add_f32 v[16:17], v[108:109], v[16:17]
	v_exp_f32_e32 v99, v233
	v_exp_f32_e32 v56, v236
	v_exp_f32_e32 v55, v235
	v_pk_add_f32 v[232:233], v[166:167], v[212:213] op_sel:[0,1] op_sel_hi:[1,1] neg_lo:[0,1] neg_hi:[0,1]
	v_pk_add_f32 v[16:17], v[58:59], v[16:17]
	v_exp_f32_e32 v57, v237
	v_exp_f32_e32 v40, v233
	v_pk_add_f32 v[16:17], v[62:63], v[16:17]
	v_exp_f32_e32 v41, v232
	v_pk_add_f32 v[232:233], v[168:169], v[212:213] op_sel:[0,1] op_sel_hi:[1,1] neg_lo:[0,1] neg_hi:[0,1]
	v_pk_add_f32 v[16:17], v[70:71], v[16:17]
	v_exp_f32_e32 v42, v232
	v_pk_add_f32 v[16:17], v[98:99], v[16:17]
	v_exp_f32_e32 v43, v233
	v_pk_add_f32 v[232:233], v[170:171], v[212:213] op_sel:[0,1] op_sel_hi:[1,1] neg_lo:[0,1] neg_hi:[0,1]
	v_pk_add_f32 v[0:1], v[56:57], v[16:17]
	v_exp_f32_e32 v44, v232
	v_pk_add_f32 v[0:1], v[60:61], v[0:1]
	v_exp_f32_e32 v45, v233
	v_pk_add_f32 v[232:233], v[172:173], v[212:213] op_sel:[0,1] op_sel_hi:[1,1] neg_lo:[0,1] neg_hi:[0,1]
	v_pk_add_f32 v[0:1], v[66:67], v[0:1]
	v_exp_f32_e32 v46, v232
	v_pk_add_f32 v[0:1], v[74:75], v[0:1]
	v_exp_f32_e32 v47, v233
	v_pk_add_f32 v[232:233], v[174:175], v[212:213] op_sel:[0,1] op_sel_hi:[1,1] neg_lo:[0,1] neg_hi:[0,1]
	v_pk_add_f32 v[0:1], v[48:49], v[0:1]
	v_exp_f32_e32 v32, v232
	v_pk_add_f32 v[0:1], v[50:51], v[0:1]
	v_exp_f32_e32 v33, v233
	v_pk_add_f32 v[232:233], v[176:177], v[212:213] op_sel:[0,1] op_sel_hi:[1,1] neg_lo:[0,1] neg_hi:[0,1]
	v_pk_add_f32 v[0:1], v[52:53], v[0:1]
	v_exp_f32_e32 v34, v232
	v_pk_add_f32 v[0:1], v[54:55], v[0:1]
	v_exp_f32_e32 v35, v233
	v_pk_add_f32 v[232:233], v[178:179], v[212:213] op_sel:[0,1] op_sel_hi:[1,1] neg_lo:[0,1] neg_hi:[0,1]
	v_pk_add_f32 v[0:1], v[40:41], v[0:1]
	v_exp_f32_e32 v36, v232
	v_pk_add_f32 v[0:1], v[42:43], v[0:1]
	v_exp_f32_e32 v37, v233
	v_pk_add_f32 v[232:233], v[180:181], v[212:213] op_sel:[0,1] op_sel_hi:[1,1] neg_lo:[0,1] neg_hi:[0,1]
	v_pk_add_f32 v[0:1], v[44:45], v[0:1]
	v_exp_f32_e32 v38, v232
	v_pk_add_f32 v[0:1], v[46:47], v[0:1]
	v_exp_f32_e32 v39, v233
	v_pk_add_f32 v[0:1], v[32:33], v[0:1]
	v_cvt_pk_bf16_f32 v16, v110, v111
	v_cvt_pk_bf16_f32 v17, v154, v155
	v_add_u32_e32 v154, 0x9000, v207
	v_pk_add_f32 v[0:1], v[34:35], v[0:1]
	v_cvt_pk_bf16_f32 v18, v160, v161
	v_cvt_pk_bf16_f32 v19, v164, v165
	v_add_u32_e32 v160, 0xd000, v207
	v_pk_add_f32 v[0:1], v[36:37], v[0:1]
	ds_read2_b64 v[20:23], v160 offset0:32 offset1:34
	v_pk_add_f32 v[0:1], v[38:39], v[0:1]
	s_nop 0
	v_add_f32_e32 v0, v0, v1
	ds_bpermute_b32 v1, v188, v0
	s_waitcnt lgkmcnt(0)
	v_add_f32_e32 v0, v0, v1
	v_sub_f32_e32 v1, v96, v213
	v_exp_f32_e32 v1, v1
	s_nop 0
	v_add_f32_e32 v96, v1, v0
	ds_read2_b64 v[0:3], v154 offset1:2
	v_cvt_pk_bf16_f32 v110, v102, v103
	v_cvt_pk_bf16_f32 v111, v112, v113
	v_cvt_pk_bf16_f32 v112, v156, v157
	v_cvt_pk_bf16_f32 v113, v162, v163
	ds_read2_b64 v[154:157], v154 offset0:4 offset1:6
	s_waitcnt lgkmcnt(1)
	v_mfma_f32_32x32x16_bf16 v[0:15], v[0:3], v[16:19], 0
	s_waitcnt lgkmcnt(0)
	v_mfma_f32_32x32x16_bf16 v[0:15], v[154:157], v[110:113], v[0:15]
	ds_read2_b64 v[154:157], v160 offset0:36 offset1:38
	v_mfma_f32_32x32x16_bf16 v[16:31], v[20:23], v[16:19], 0
	s_waitcnt lgkmcnt(0)
	v_mfma_f32_32x32x16_bf16 v[16:31], v[154:157], v[110:113], v[16:31]
	v_cvt_pk_bf16_f32 v110, v78, v79
	v_add_u32_e32 v78, 0x9000, v208
	v_cvt_pk_bf16_f32 v111, v106, v107
	v_cvt_pk_bf16_f32 v112, v118, v119
	v_cvt_pk_bf16_f32 v113, v158, v159
	ds_read2_b64 v[154:157], v78 offset1:2
	v_add_u32_e32 v106, 0xd000, v208
	s_waitcnt lgkmcnt(0)
	v_mfma_f32_32x32x16_bf16 v[0:15], v[154:157], v[110:113], v[0:15]
	ds_read2_b64 v[154:157], v106 offset0:32 offset1:34
	v_cvt_pk_bf16_f32 v102, v68, v69
	v_cvt_pk_bf16_f32 v103, v76, v77
	v_cvt_pk_bf16_f32 v104, v104, v105
	v_cvt_pk_bf16_f32 v105, v114, v115
	ds_read2_b64 v[76:79], v78 offset0:4 offset1:6
	s_waitcnt lgkmcnt(0)
	v_mfma_f32_32x32x16_bf16 v[0:15], v[76:79], v[102:105], v[0:15]
	ds_read2_b64 v[76:79], v106 offset0:36 offset1:38
	v_mfma_f32_32x32x16_bf16 v[16:31], v[154:157], v[110:113], v[16:31]
	s_waitcnt lgkmcnt(0)
	v_mfma_f32_32x32x16_bf16 v[16:31], v[76:79], v[102:105], v[16:31]
	v_cvt_pk_bf16_f32 v76, v64, v65
	v_add_u32_e32 v64, 0x9000, v209
	v_cvt_pk_bf16_f32 v77, v72, v73
	v_cvt_pk_bf16_f32 v78, v100, v101
	v_cvt_pk_bf16_f32 v79, v108, v109
	ds_read2_b64 v[100:103], v64 offset1:2
	v_add_u32_e32 v72, 0xd000, v209
	s_waitcnt lgkmcnt(0)
	v_mfma_f32_32x32x16_bf16 v[0:15], v[100:103], v[76:79], v[0:15]
	ds_read2_b64 v[100:103], v72 offset0:32 offset1:34
	v_cvt_pk_bf16_f32 v68, v58, v59
	v_cvt_pk_bf16_f32 v69, v62, v63
	v_cvt_pk_bf16_f32 v70, v70, v71
	v_cvt_pk_bf16_f32 v71, v98, v99
	ds_read2_b64 v[62:65], v64 offset0:4 offset1:6
	s_waitcnt lgkmcnt(0)
	v_mfma_f32_32x32x16_bf16 v[0:15], v[62:65], v[68:71], v[0:15]
	ds_read2_b64 v[62:65], v72 offset0:36 offset1:38
	v_cvt_pk_bf16_f32 v56, v56, v57
	v_cvt_pk_bf16_f32 v57, v60, v61
	v_cvt_pk_bf16_f32 v58, v66, v67
	v_cvt_pk_bf16_f32 v59, v74, v75
	v_mfma_f32_32x32x16_bf16 v[16:31], v[100:103], v[76:79], v[16:31]
	s_waitcnt lgkmcnt(0)
	v_mfma_f32_32x32x16_bf16 v[16:31], v[62:65], v[68:71], v[16:31]
	v_add_u32_e32 v64, 0x9000, v210
	ds_read2_b64 v[60:63], v64 offset1:2
	v_add_u32_e32 v65, 0xd000, v210
	s_waitcnt lgkmcnt(0)
	v_mfma_f32_32x32x16_bf16 v[0:15], v[60:63], v[56:59], v[0:15]
	ds_read2_b64 v[60:63], v65 offset0:32 offset1:34
	v_cvt_pk_bf16_f32 v48, v48, v49
	v_cvt_pk_bf16_f32 v49, v50, v51
	v_cvt_pk_bf16_f32 v50, v52, v53
	v_cvt_pk_bf16_f32 v51, v54, v55
	ds_read2_b64 v[52:55], v64 offset0:4 offset1:6
	s_waitcnt lgkmcnt(0)
	v_mfma_f32_32x32x16_bf16 v[0:15], v[52:55], v[48:51], v[0:15]
	ds_read2_b64 v[52:55], v65 offset0:36 offset1:38
	v_cvt_pk_bf16_f32 v40, v40, v41
	v_cvt_pk_bf16_f32 v41, v42, v43
	v_cvt_pk_bf16_f32 v42, v44, v45
	v_cvt_pk_bf16_f32 v43, v46, v47
	v_mfma_f32_32x32x16_bf16 v[16:31], v[60:63], v[56:59], v[16:31]
	s_waitcnt lgkmcnt(0)
	v_mfma_f32_32x32x16_bf16 v[16:31], v[52:55], v[48:51], v[16:31]
	v_add_u32_e32 v48, 0x9000, v211
	ds_read2_b64 v[44:47], v48 offset1:2
	v_add_u32_e32 v49, 0xd000, v211
	s_waitcnt lgkmcnt(0)
	v_mfma_f32_32x32x16_bf16 v[0:15], v[44:47], v[40:43], v[0:15]
	ds_read2_b64 v[44:47], v49 offset0:32 offset1:34
	v_cvt_pk_bf16_f32 v32, v32, v33
	v_cvt_pk_bf16_f32 v33, v34, v35
	v_cvt_pk_bf16_f32 v34, v36, v37
	v_cvt_pk_bf16_f32 v35, v38, v39
	ds_read2_b64 v[36:39], v48 offset0:4 offset1:6
	s_waitcnt lgkmcnt(0)
	v_mfma_f32_32x32x16_bf16 v[0:15], v[36:39], v[32:35], v[0:15]
	ds_read2_b64 v[36:39], v49 offset0:36 offset1:38
	v_mfma_f32_32x32x16_bf16 v[16:31], v[44:47], v[40:43], v[16:31]
	s_waitcnt lgkmcnt(0)
	v_mfma_f32_32x32x16_bf16 v[16:31], v[36:39], v[32:35], v[16:31]
	v_div_scale_f32 v32, s[68:69], v96, v96, 1.0
	v_rcp_f32_e32 v33, v32
	s_nop 0
	v_fma_f32 v34, -v32, v33, 1.0
	v_fmac_f32_e32 v33, v34, v33
	v_div_scale_f32 v34, vcc, 1.0, v96, 1.0
	v_mul_f32_e32 v35, v34, v33
	v_fma_f32 v36, -v32, v35, v34
	v_fmac_f32_e32 v35, v36, v33
	v_fma_f32 v32, -v32, v35, v34
	v_div_fmas_f32 v32, v32, v33, v35
	v_div_fixup_f32 v34, v32, v96, 1.0
	v_mul_f32_e32 v0, v0, v34
	v_mul_f32_e32 v1, v1, v34
	v_cvt_pk_bf16_f32 v0, v0, v1
	v_mul_f32_e32 v1, v2, v34
	v_mad_i64_i32 v[32:33], s[68:69], v153, s65, v[116:117]
	v_and_b32_e32 v36, 63, v251
	v_and_b32_e32 v35, 31, v251
	v_lshrrev_b32_e32 v37, 5, v36
	v_lshlrev_b32_e32 v37, 3, v37
	s_movk_i32 s58, 0x90
	v_mad_u32_u24 v35, v35, s58, v37
	s_movk_i32 s59, 0x1200
	v_mad_u32_u24 v35, v254, s59, v35
	v_add_u32_e32 v35, 0x12000, v35
	v_lshrrev_b32_e32 v37, 3, v36
	v_and_b32_e32 v40, 7, v36
	v_lshlrev_b32_e32 v40, 4, v40
	v_mad_u32_u24 v36, v37, s58, v40
	v_mad_u32_u24 v36, v254, s59, v36
	v_add_u32_e32 v36, 0x12000, v36
	s_movk_i32 s58, 0xc00
	v_mad_u32_u24 v37, v37, s58, v40
	s_cmpk_gt_i32 s33, 0x3ff
	s_cbranch_scc1 .Lt8_skip
	s_lshl_b32 s58, s33, 5
	s_and_b32 s58, s58, 0x780
	s_addk_i32 s58, 0xff80
	v_add_u32_e32 v230, s58, v250
	v_lshl_add_u32 v230, v230, 7, v248
	v_max_i32_e32 v231, v248, v230
	global_load_dwordx4 v[116:119], v231, s[82:83]
	global_load_dwordx4 v[154:157], v231, s[92:93]
	v_add_u32_e32 v230, 0x400, v230
	v_max_i32_e32 v231, v248, v230
	global_load_dwordx4 v[44:47], v231, s[82:83]
	global_load_dwordx4 v[68:71], v231, s[92:93]
	v_add_u32_e32 v230, 0x400, v230
	v_max_i32_e32 v231, v248, v230
	global_load_dwordx4 v[158:161], v231, s[82:83]
	global_load_dwordx4 v[162:165], v231, s[92:93]
	v_add_u32_e32 v230, 0x400, v230
	v_max_i32_e32 v231, v248, v230
	global_load_dwordx4 v[40:43], v231, s[82:83]
	global_load_dwordx4 v[48:51], v231, s[92:93]
.Lt8_skip:
	v_readfirstlane_b32 s56, v32
	v_readfirstlane_b32 s57, v33
	v_mul_f32_e32 v2, v3, v34
	v_cvt_pk_bf16_f32 v1, v1, v2
	ds_write_b64 v35, v[0:1]
	v_mul_f32_e32 v0, v4, v34
	v_mul_f32_e32 v1, v5, v34
	v_cvt_pk_bf16_f32 v0, v0, v1
	v_mul_f32_e32 v1, v6, v34
	v_mul_f32_e32 v2, v7, v34
	v_cvt_pk_bf16_f32 v1, v1, v2
	ds_write_b64 v35, v[0:1] offset:16
	v_mul_f32_e32 v0, v8, v34
	v_mul_f32_e32 v1, v9, v34
	v_cvt_pk_bf16_f32 v0, v0, v1
	v_mul_f32_e32 v1, v10, v34
	v_mul_f32_e32 v2, v11, v34
	v_cvt_pk_bf16_f32 v1, v1, v2
	ds_write_b64 v35, v[0:1] offset:32
	v_mul_f32_e32 v0, v12, v34
	v_mul_f32_e32 v1, v13, v34
	v_cvt_pk_bf16_f32 v0, v0, v1
	v_mul_f32_e32 v1, v14, v34
	v_mul_f32_e32 v2, v15, v34
	v_cvt_pk_bf16_f32 v1, v1, v2
	ds_write_b64 v35, v[0:1] offset:48
	v_mul_f32_e32 v0, v16, v34
	v_mul_f32_e32 v1, v17, v34
	v_cvt_pk_bf16_f32 v0, v0, v1
	v_mul_f32_e32 v1, v18, v34
	v_mul_f32_e32 v2, v19, v34
	v_cvt_pk_bf16_f32 v1, v1, v2
	ds_write_b64 v35, v[0:1] offset:64
	v_mul_f32_e32 v0, v20, v34
	v_mul_f32_e32 v1, v21, v34
	v_cvt_pk_bf16_f32 v0, v0, v1
	v_mul_f32_e32 v1, v22, v34
	v_mul_f32_e32 v2, v23, v34
	v_cvt_pk_bf16_f32 v1, v1, v2
	ds_write_b64 v35, v[0:1] offset:80
	v_mul_f32_e32 v0, v24, v34
	v_mul_f32_e32 v1, v25, v34
	v_cvt_pk_bf16_f32 v0, v0, v1
	v_mul_f32_e32 v1, v26, v34
	v_mul_f32_e32 v2, v27, v34
	v_cvt_pk_bf16_f32 v1, v1, v2
	ds_write_b64 v35, v[0:1] offset:96
	v_mul_f32_e32 v0, v28, v34
	v_mul_f32_e32 v1, v29, v34
	v_cvt_pk_bf16_f32 v0, v0, v1
	v_mul_f32_e32 v1, v30, v34
	s_andn2_b64 vcc, exec, s[76:77]
	v_mul_f32_e32 v2, v31, v34
	v_cvt_pk_bf16_f32 v1, v1, v2
	ds_write_b64 v35, v[0:1] offset:112
	s_waitcnt lgkmcnt(0)
	ds_read_b128 v[0:3], v36
	ds_read_b128 v[4:7], v36 offset:1152
	ds_read_b128 v[8:11], v36 offset:2304
	ds_read_b128 v[12:15], v36 offset:3456
	s_waitcnt lgkmcnt(3)
	global_store_dwordx4 v37, v[0:3], s[56:57]
	s_add_u32 s56, s56, 0x6000
	s_addc_u32 s57, s57, 0
	s_waitcnt lgkmcnt(2)
	global_store_dwordx4 v37, v[4:7], s[56:57]
	s_add_u32 s56, s56, 0x6000
	s_addc_u32 s57, s57, 0
	s_waitcnt lgkmcnt(1)
	global_store_dwordx4 v37, v[8:11], s[56:57]
	s_add_u32 s56, s56, 0x6000
	s_addc_u32 s57, s57, 0
	s_waitcnt lgkmcnt(0)
	global_store_dwordx4 v37, v[12:15], s[56:57]
	s_nop 1
	s_setprio 0
	s_cbranch_vccz .Lattn_exit
.LBB0_348:
	ds_read_b128 v[24:27], v242 offset:16
	ds_read_b128 v[28:31], v242 offset:144
	s_bfe_u32 s88, s33, 0x40002
	s_lshl_b32 s68, s88, 7
	ds_read_b128 v[72:75], v242
	ds_read_b128 v[16:19], v242 offset:48
	ds_read_b128 v[32:35], v242 offset:32
	ds_read_b128 v[20:23], v242 offset:176
	ds_read_b128 v[36:39], v242 offset:160
	ds_read_b128 v[76:79], v242 offset:128
	s_mov_b32 s0, s97
	s_and_b32 s97, s90, 12
	s_and_b32 s89, s96, 0xfffff800
	v_readlane_b32 s55, v255, 14
	s_waitcnt vmcnt(20)
	v_and_b32_e32 v224, 63, v251
	v_lshrrev_b32_e32 v225, 3, v224
	s_movk_i32 s58, 0x90
	v_mul_u32_u24_e32 v226, 0x1200, v254
	v_add_u32_e32 v226, 0x12000, v226
	v_and_b32_e32 v227, 7, v224
	v_lshlrev_b32_e32 v227, 4, v227
	v_mad_u32_u24 v227, v225, s58, v227
	v_add_u32_e32 v227, v227, v226
	v_lshrrev_b32_e32 v225, 1, v224
	v_and_b32_e32 v224, 1, v224
	v_lshlrev_b32_e32 v224, 5, v224
	v_mad_u32_u24 v224, v225, s58, v224
	v_add_u32_e32 v224, v224, v226
	ds_write_b128 v227, v[80:83]
	ds_write_b128 v227, v[84:87] offset:1152
	ds_write_b128 v227, v[88:91] offset:2304
	ds_write_b128 v227, v[92:95] offset:3456
	ds_read_b128 v[80:83], v224
	ds_read_b128 v[84:87], v224 offset:16
	ds_read_b128 v[92:95], v224 offset:64
	ds_read_b128 v[88:91], v224 offset:80
	s_waitcnt lgkmcnt(0)
	v_and_b32_e32 v64, 0xffff0000, v84
	v_lshlrev_b32_e32 v65, 16, v84
	v_and_b32_e32 v60, 0xffff0000, v85
	v_lshlrev_b32_e32 v61, 16, v85
	s_add_i32 s97, s97, s55
	v_or_b32_e32 v8, s89, v185
	v_and_b32_e32 v66, 0xffff0000, v88
	v_lshlrev_b32_e32 v67, 16, v88
	v_and_b32_e32 v62, 0xffff0000, v89
	v_lshlrev_b32_e32 v63, 16, v89
	v_pk_mul_f32 v[0:1], v[64:65], v[64:65]
	v_pk_mul_f32 v[2:3], v[60:61], v[60:61]
	v_or_b32_e32 v8, s68, v8
	s_lshl_b32 s94, s97, 7
	v_and_b32_e32 v56, 0xffff0000, v86
	v_lshlrev_b32_e32 v57, 16, v86
	v_and_b32_e32 v52, 0xffff0000, v87
	v_lshlrev_b32_e32 v53, 16, v87
	v_pk_fma_f32 v[214:215], v[66:67], v[66:67], v[0:1]
	v_pk_fma_f32 v[216:217], v[62:63], v[62:63], v[2:3]
	v_or_b32_e32 v2, 32, v8
	v_and_b32_e32 v58, 0xffff0000, v90
	v_lshlrev_b32_e32 v59, 16, v90
	v_and_b32_e32 v54, 0xffff0000, v91
	v_lshlrev_b32_e32 v55, 16, v91
	v_pk_mul_f32 v[4:5], v[56:57], v[56:57]
	v_pk_mul_f32 v[6:7], v[52:53], v[52:53]
	v_pk_fma_f32 v[218:219], v[58:59], v[58:59], v[4:5]
	v_pk_fma_f32 v[220:221], v[54:55], v[54:55], v[6:7]
	v_readlane_b32 s78, v255, 6
	v_readlane_b32 s79, v255, 7
	s_or_b32 s58, s89, s68
	s_or_b32 s58, s58, s91
	v_and_b32_e32 v231, 7, v250
	v_add_u32_e32 v231, s58, v231
	v_add_u32_e32 v230, s94, v248
	v_mad_u32_u24 v230, v231, s65, v230
	s_nop 0
	global_load_dwordx4 v[0:3], v230, s[78:79]
	v_add_u32_e32 v230, 0x6000, v230
	global_load_dwordx4 v[4:7], v230, s[78:79]
	v_add_u32_e32 v230, 0x6000, v230
	global_load_dwordx4 v[8:11], v230, s[78:79]
	v_add_u32_e32 v230, 0x6000, v230
	global_load_dwordx4 v[12:15], v230, s[78:79]
	v_add_u32_e32 v230, 0x6000, v230
	global_load_dwordx4 v[100:103], v230, s[78:79]
	v_add_u32_e32 v230, 0x6000, v230
	global_load_dwordx4 v[104:107], v230, s[78:79]
	v_add_u32_e32 v230, 0x6000, v230
	global_load_dwordx4 v[108:111], v230, s[78:79]
	v_add_u32_e32 v230, 0x6000, v230
	global_load_dwordx4 v[112:115], v230, s[78:79]
	v_lshlrev_b32_e32 v239, 16, v92
	v_lshlrev_b32_e32 v238, 16, v80
	v_and_b32_e32 v245, 0xffff0000, v92
	v_and_b32_e32 v244, 0xffff0000, v80
	v_lshlrev_b32_e32 v229, 16, v93
	v_lshlrev_b32_e32 v228, 16, v81
	v_pk_mul_f32 v[240:241], v[238:239], v[238:239]
	v_pk_mul_f32 v[246:247], v[244:245], v[244:245]
	v_pk_mul_f32 v[230:231], v[228:229], v[228:229]
	v_and_b32_e32 v235, 0xffff0000, v93
	v_and_b32_e32 v234, 0xffff0000, v81
	v_lshlrev_b32_e32 v171, 16, v94
	v_lshlrev_b32_e32 v170, 16, v82
	v_pk_mul_f32 v[236:237], v[234:235], v[234:235]
	v_and_b32_e32 v173, 0xffff0000, v94
	v_and_b32_e32 v172, 0xffff0000, v82
	v_pk_mul_f32 v[178:179], v[170:171], v[170:171]
	v_lshlrev_b32_e32 v167, 16, v95
	v_lshlrev_b32_e32 v166, 16, v83
	v_pk_mul_f32 v[180:181], v[172:173], v[172:173]
	v_and_b32_e32 v169, 0xffff0000, v95
	v_and_b32_e32 v168, 0xffff0000, v83
	v_pk_mul_f32 v[174:175], v[166:167], v[166:167]
	v_pk_mul_f32 v[176:177], v[168:169], v[168:169]
	v_readlane_b32 s76, v255, 1
	s_add_i32 s33, s33, s76
	v_readlane_b32 s77, v255, 2
	s_cmpk_gt_i32 s33, 0x3ff
	s_cselect_b64 s[76:77], -1, 0
	s_waitcnt lgkmcnt(0)
	v_mov_b32_e32 v98, v26
	s_waitcnt lgkmcnt(0)
	v_mov_b32_e32 v223, v28
	v_add_f32_e32 v26, v247, v246
	v_add_f32_e32 v28, v241, v240
	v_add_f32_e32 v26, v28, v26
	v_add_f32_e32 v28, v231, v230
	v_mov_b32_e32 v222, v24
	v_add_f32_e32 v24, v237, v236
	v_add_f32_e32 v26, v28, v26
	v_add_f32_e32 v24, v24, v26
	v_add_f32_e32 v26, v179, v178
	v_add_f32_e32 v24, v26, v24
	v_add_f32_e32 v26, v181, v180
	v_add_f32_e32 v24, v26, v24
	v_add_f32_e32 v26, v175, v174
	v_add_f32_e32 v24, v26, v24
	v_add_f32_e32 v26, v177, v176
	v_add_f32_e32 v24, v26, v24
	v_add_f32_e32 v24, v215, v24
	v_add_f32_e32 v24, v214, v24
	v_add_f32_e32 v24, v217, v24
	v_add_f32_e32 v24, v216, v24
	v_add_f32_e32 v24, v219, v24
	v_add_f32_e32 v24, v218, v24
	v_add_f32_e32 v24, v221, v24
	v_add_f32_e32 v24, v220, v24
	ds_bpermute_b32 v26, v187, v24
	s_waitcnt vmcnt(12)
	ds_write_b128 v227, v[116:119]
	ds_write_b128 v227, v[44:47] offset:1152
	ds_write_b128 v227, v[158:161] offset:2304
	ds_write_b128 v227, v[40:43] offset:3456
	v_and_b32_e32 v225, 63, v251
	v_lshrrev_b32_e32 v224, 1, v225
	v_and_b32_e32 v225, 1, v225
	v_lshlrev_b32_e32 v225, 6, v225
	v_mul_u32_u24_e32 v224, 0x90, v224
	v_add3_u32 v225, v224, v225, v226
	ds_read_b128 v[116:119], v225
	ds_read_b128 v[44:47], v225 offset:16
	ds_read_b128 v[158:161], v225 offset:32
	ds_read_b128 v[40:43], v225 offset:48
	ds_write_b128 v227, v[154:157]
	ds_write_b128 v227, v[68:71] offset:1152
	ds_write_b128 v227, v[162:165] offset:2304
	ds_write_b128 v227, v[48:51] offset:3456
	ds_read_b128 v[154:157], v225
	ds_read_b128 v[68:71], v225 offset:16
	ds_read_b128 v[162:165], v225 offset:32
	ds_read_b128 v[48:51], v225 offset:48
	s_waitcnt lgkmcnt(0)
	s_waitcnt lgkmcnt(0)
	v_mov_b32_e32 v176, v72
	s_waitcnt lgkmcnt(0)
	v_mov_b32_e32 v177, v76
	v_mov_b32_e32 v178, v116
	v_mov_b32_e32 v179, v154
	s_waitcnt lgkmcnt(0)
	v_add_f32_e32 v24, v24, v26
	v_fmamk_f32 v24, v24, 0x3c800000, v189
	v_rsq_f32_e32 v24, v24
	v_mov_b32_e32 v76, v73
	v_mov_b32_e32 v232, v74
	v_mov_b32_e32 v233, v78
	v_pk_mul_f32 v[180:181], v[24:25], v[238:239] op_sel_hi:[0,1]
	v_pk_mul_f32 v[176:177], v[176:177], v[180:181]
	v_mov_b32_e32 v174, v118
	v_pk_mul_f32 v[178:179], v[178:179], v[176:177]
	v_mov_b32_e32 v175, v156
	v_sub_f32_e32 v96, v178, v179
	v_mov_b32_e32 v178, v154
	v_mov_b32_e32 v179, v116
	v_pk_mul_f32 v[176:177], v[178:179], v[176:177]
	v_mov_b32_e32 v154, v117
	v_add_f32_e32 v153, v177, v176
	v_pk_mul_f32 v[176:177], v[24:25], v[244:245] op_sel_hi:[0,1]
	v_pk_mul_f32 v[72:73], v[76:77], v[176:177]
	v_mov_b32_e32 v116, v155
	v_pk_mul_f32 v[76:77], v[154:155], v[72:73]
	v_pk_mul_f32 v[72:73], v[116:117], v[72:73]
	v_sub_f32_e32 v154, v76, v77
	v_add_f32_e32 v116, v73, v72
	v_pk_mul_f32 v[72:73], v[24:25], v[228:229] op_sel_hi:[0,1]
	v_pk_mul_f32 v[72:73], v[232:233], v[72:73]
	v_mov_b32_e32 v78, v75
	v_pk_mul_f32 v[76:77], v[174:175], v[72:73]
	v_mov_b32_e32 v226, v44
	v_sub_f32_e32 v117, v76, v77
	v_mov_b32_e32 v76, v156
	v_mov_b32_e32 v77, v118
	v_pk_mul_f32 v[72:73], v[76:77], v[72:73]
	v_mov_b32_e32 v156, v119
	v_add_f32_e32 v76, v73, v72
	v_pk_mul_f32 v[72:73], v[24:25], v[234:235] op_sel_hi:[0,1]
	v_pk_mul_f32 v[72:73], v[78:79], v[72:73]
	v_mov_b32_e32 v118, v157
	v_pk_mul_f32 v[74:75], v[156:157], v[72:73]
	v_pk_mul_f32 v[72:73], v[118:119], v[72:73]
	v_mov_b32_e32 v227, v68
	v_add_f32_e32 v78, v73, v72
	v_pk_mul_f32 v[72:73], v[24:25], v[170:171] op_sel_hi:[0,1]
	v_pk_mul_f32 v[72:73], v[72:73], v[222:223]
	v_sub_f32_e32 v77, v74, v75
	v_pk_mul_f32 v[74:75], v[72:73], v[226:227]
	v_mov_b32_e32 v28, v25
	v_sub_f32_e32 v79, v74, v75
	v_mov_b32_e32 v74, v68
	v_mov_b32_e32 v75, v44
	v_pk_mul_f32 v[72:73], v[72:73], v[74:75]
	v_mov_b32_e32 v68, v45
	v_add_f32_e32 v74, v73, v72
	v_pk_mul_f32 v[72:73], v[24:25], v[172:173] op_sel_hi:[0,1]
	v_pk_mul_f32 v[28:29], v[72:73], v[28:29]
	v_mov_b32_e32 v44, v69
	v_pk_mul_f32 v[72:73], v[28:29], v[68:69]
	v_pk_mul_f32 v[28:29], v[28:29], v[44:45]
	v_sub_f32_e32 v25, v72, v73
	v_mov_b32_e32 v99, v30
	v_add_f32_e32 v68, v29, v28
	v_pk_mul_f32 v[28:29], v[24:25], v[166:167] op_sel_hi:[0,1]
	v_mov_b32_e32 v224, v46
	v_mov_b32_e32 v225, v70
	v_pk_mul_f32 v[28:29], v[28:29], v[98:99]
	v_mov_b32_e32 v30, v27
	v_pk_mul_f32 v[44:45], v[28:29], v[224:225]
	s_and_b64 vcc, exec, s[76:77]
	v_sub_f32_e32 v69, v44, v45
	v_mov_b32_e32 v44, v70
	v_mov_b32_e32 v45, v46
	v_pk_mul_f32 v[28:29], v[28:29], v[44:45]
	v_mov_b32_e32 v70, v47
	v_add_f32_e32 v44, v29, v28
	v_pk_mul_f32 v[28:29], v[24:25], v[168:169] op_sel_hi:[0,1]
	v_pk_mul_f32 v[26:27], v[28:29], v[30:31]
	v_mov_b32_e32 v46, v71
	v_pk_mul_f32 v[28:29], v[26:27], v[70:71]
	v_pk_mul_f32 v[26:27], v[26:27], v[46:47]
	v_sub_f32_e32 v30, v28, v29
	v_add_f32_e32 v31, v27, v26
	v_mov_b32_e32 v26, v65
	v_mov_b32_e32 v27, v67
	v_pk_mul_f32 v[26:27], v[24:25], v[26:27] op_sel_hi:[0,1]
	v_mov_b32_e32 v28, v32
	v_mov_b32_e32 v29, v36
	v_pk_mul_f32 v[26:27], v[26:27], v[28:29]
	v_mov_b32_e32 v28, v158
	v_mov_b32_e32 v29, v162
	v_pk_mul_f32 v[28:29], v[26:27], v[28:29]
	v_mov_b32_e32 v65, v66
	v_sub_f32_e32 v32, v28, v29
	v_mov_b32_e32 v28, v162
	v_mov_b32_e32 v29, v158
	v_pk_mul_f32 v[26:27], v[26:27], v[28:29]
	v_mov_b32_e32 v36, v33
	v_add_f32_e32 v45, v27, v26
	v_pk_mul_f32 v[26:27], v[24:25], v[64:65] op_sel_hi:[0,1]
	v_pk_mul_f32 v[26:27], v[26:27], v[36:37]
	v_mov_b32_e32 v162, v159
	v_mov_b32_e32 v158, v163
	v_pk_mul_f32 v[28:29], v[26:27], v[162:163]
	v_pk_mul_f32 v[26:27], v[26:27], v[158:159]
	v_sub_f32_e32 v33, v28, v29
	v_add_f32_e32 v36, v27, v26
	v_mov_b32_e32 v26, v61
	v_mov_b32_e32 v27, v63
	v_pk_mul_f32 v[26:27], v[24:25], v[26:27] op_sel_hi:[0,1]
	v_mov_b32_e32 v28, v34
	v_mov_b32_e32 v29, v38
	v_pk_mul_f32 v[26:27], v[26:27], v[28:29]
	v_mov_b32_e32 v28, v160
	v_mov_b32_e32 v29, v164
	v_pk_mul_f32 v[28:29], v[26:27], v[28:29]
	v_mov_b32_e32 v61, v62
	v_sub_f32_e32 v34, v28, v29
	v_mov_b32_e32 v28, v164
	v_mov_b32_e32 v29, v160
	v_pk_mul_f32 v[26:27], v[26:27], v[28:29]
	v_mov_b32_e32 v38, v35
	v_add_f32_e32 v37, v27, v26
	v_pk_mul_f32 v[26:27], v[24:25], v[60:61] op_sel_hi:[0,1]
	v_pk_mul_f32 v[26:27], v[26:27], v[38:39]
	v_mov_b32_e32 v164, v161
	v_mov_b32_e32 v160, v165
	v_pk_mul_f32 v[28:29], v[26:27], v[164:165]
	v_pk_mul_f32 v[26:27], v[26:27], v[160:161]
	v_sub_f32_e32 v35, v28, v29
	v_add_f32_e32 v38, v27, v26
	v_mov_b32_e32 v26, v57
	v_mov_b32_e32 v27, v59
	v_pk_mul_f32 v[26:27], v[24:25], v[26:27] op_sel_hi:[0,1]
	v_mov_b32_e32 v28, v16
	v_mov_b32_e32 v29, v20
	v_pk_mul_f32 v[26:27], v[26:27], v[28:29]
	v_mov_b32_e32 v28, v40
	v_mov_b32_e32 v29, v48
	v_pk_mul_f32 v[28:29], v[26:27], v[28:29]
	v_mov_b32_e32 v57, v58
	v_sub_f32_e32 v39, v28, v29
	v_mov_b32_e32 v28, v48
	v_mov_b32_e32 v29, v40
	v_pk_mul_f32 v[26:27], v[26:27], v[28:29]
	v_mov_b32_e32 v20, v17
	v_add_f32_e32 v28, v27, v26
	v_pk_mul_f32 v[26:27], v[24:25], v[56:57] op_sel_hi:[0,1]
	v_pk_mul_f32 v[16:17], v[26:27], v[20:21]
	v_mov_b32_e32 v48, v41
	v_mov_b32_e32 v40, v49
	v_pk_mul_f32 v[20:21], v[16:17], v[48:49]
	v_pk_mul_f32 v[16:17], v[16:17], v[40:41]
	v_sub_f32_e32 v26, v20, v21
	v_add_f32_e32 v27, v17, v16
	v_mov_b32_e32 v16, v53
	v_mov_b32_e32 v17, v55
	v_pk_mul_f32 v[16:17], v[24:25], v[16:17] op_sel_hi:[0,1]
	v_mov_b32_e32 v20, v18
	v_mov_b32_e32 v21, v22
	v_pk_mul_f32 v[16:17], v[16:17], v[20:21]
	v_mov_b32_e32 v20, v42
	v_mov_b32_e32 v21, v50
	v_pk_mul_f32 v[20:21], v[16:17], v[20:21]
	v_mov_b32_e32 v53, v54
	v_sub_f32_e32 v29, v20, v21
	v_mov_b32_e32 v20, v50
	v_mov_b32_e32 v21, v42
	v_pk_mul_f32 v[16:17], v[16:17], v[20:21]
	v_mov_b32_e32 v22, v19
	v_add_f32_e32 v20, v17, v16
	v_pk_mul_f32 v[16:17], v[24:25], v[52:53] op_sel_hi:[0,1]
	v_pk_mul_f32 v[16:17], v[16:17], v[22:23]
	v_mov_b32_e32 v50, v43
	v_mov_b32_e32 v42, v51
	v_pk_mul_f32 v[18:19], v[16:17], v[50:51]
	v_pk_mul_f32 v[16:17], v[16:17], v[42:43]
	v_sub_f32_e32 v21, v18, v19
	v_add_f32_e32 v22, v17, v16
	v_cvt_pk_bf16_f32 v16, v96, v154
	v_cvt_pk_bf16_f32 v17, v117, v77
	v_cvt_pk_bf16_f32 v18, v79, v25
	v_cvt_pk_bf16_f32 v19, v69, v30
	s_barrier
	ds_write_b128 v190, v[16:19]
	v_cvt_pk_bf16_f32 v16, v32, v33
	v_cvt_pk_bf16_f32 v17, v34, v35
	v_cvt_pk_bf16_f32 v18, v39, v26
	v_cvt_pk_bf16_f32 v19, v29, v21
	ds_write_b128 v190, v[16:19] offset:16
	v_cvt_pk_bf16_f32 v16, v153, v116
	v_cvt_pk_bf16_f32 v17, v76, v78
	v_cvt_pk_bf16_f32 v18, v74, v68
	v_cvt_pk_bf16_f32 v19, v44, v31
	ds_write_b128 v190, v[16:19] offset:64
	v_cvt_pk_bf16_f32 v16, v45, v36
	v_cvt_pk_bf16_f32 v17, v37, v38
	v_cvt_pk_bf16_f32 v18, v28, v27
	v_cvt_pk_bf16_f32 v19, v20, v22
	ds_write_b128 v190, v[16:19] offset:80
	v_and_b32_e32 v20, 63, v251
	v_lshrrev_b32_e32 v21, 3, v20
	v_mul_u32_u24_e32 v21, 0x90, v21
	v_and_b32_e32 v22, 7, v20
	v_lshl_add_u32 v21, v22, 4, v21
	v_mul_u32_u24_e32 v22, 0x1200, v254
	v_add_u32_e32 v22, 0x12000, v22
	v_add_u32_e32 v21, v21, v22
	v_lshrrev_b32_e32 v23, 2, v20
	v_mul_u32_u24_e32 v23, 0x120, v23
	v_and_b32_e32 v20, 3, v20
	v_lshl_add_u32 v23, v20, 3, v23
	v_add_u32_e32 v23, v23, v22
	ds_write_b128 v21, v[122:125]
	ds_write_b128 v21, v[128:131] offset:1152
	ds_write_b128 v21, v[132:135] offset:2304
	ds_write_b128 v21, v[136:139] offset:3456
	ds_read_b64 v[122:123], v23
	ds_read_b64 v[124:125], v23 offset:32
	ds_read_b64 v[128:129], v23 offset:64
	ds_read_b64 v[130:131], v23 offset:96
	ds_read_b64 v[132:133], v23 offset:144
	ds_read_b64 v[136:137], v23 offset:176
	ds_read_b64 v[138:139], v23 offset:208
	ds_read_b64 v[140:141], v23 offset:240
	s_waitcnt lgkmcnt(0)
	v_and_b32_e32 v16, 0xffff, v122
	v_lshrrev_b32_e32 v17, 16, v122
	v_lshl_or_b32 v16, v132, 16, v16
	v_and_or_b32 v17, v132, s54, v17
	v_add_u32_e32 v18, 0x9000, v191
	ds_write2_b32 v18, v16, v17 offset1:130
	v_and_b32_e32 v16, 0xffff, v123
	v_lshrrev_b32_e32 v17, 16, v123
	v_lshl_or_b32 v16, v133, 16, v16
	v_and_or_b32 v17, v133, s54, v17
	v_add_u32_e32 v18, 0x9400, v191
	ds_write2_b32 v18, v16, v17 offset0:4 offset1:134
	v_and_b32_e32 v16, 0xffff, v124
	v_lshrrev_b32_e32 v17, 16, v124
	v_lshl_or_b32 v16, v136, 16, v16
	v_and_or_b32 v17, v136, s54, v17
	v_add_u32_e32 v18, 0xb000, v191
	ds_write2_b32 v18, v16, v17 offset0:32 offset1:162
	v_and_b32_e32 v16, 0xffff, v125
	v_lshrrev_b32_e32 v17, 16, v125
	v_lshl_or_b32 v16, v137, 16, v16
	v_and_or_b32 v17, v137, s54, v17
	v_add_u32_e32 v18, 0xb400, v191
	ds_write2_b32 v18, v16, v17 offset0:36 offset1:166
	v_and_b32_e32 v16, 0xffff, v128
	v_lshrrev_b32_e32 v17, 16, v128
	v_lshl_or_b32 v16, v138, 16, v16
	v_and_or_b32 v17, v138, s54, v17
	v_add_u32_e32 v18, 0xd000, v191
	ds_write2_b32 v18, v16, v17 offset0:64 offset1:194
	v_and_b32_e32 v16, 0xffff, v129
	v_lshrrev_b32_e32 v17, 16, v129
	v_lshl_or_b32 v16, v139, 16, v16
	v_and_or_b32 v17, v139, s54, v17
	v_add_u32_e32 v18, 0xd400, v191
	ds_write2_b32 v18, v16, v17 offset0:68 offset1:198
	v_and_b32_e32 v16, 0xffff, v130
	v_lshrrev_b32_e32 v17, 16, v130
	v_lshl_or_b32 v16, v140, 16, v16
	v_and_or_b32 v17, v140, s54, v17
	v_add_u32_e32 v18, 0xf000, v191
	ds_write2_b32 v18, v16, v17 offset0:96 offset1:226
	v_and_b32_e32 v16, 0xffff, v131
	v_lshrrev_b32_e32 v17, 16, v131
	v_lshl_or_b32 v16, v141, 16, v16
	v_and_or_b32 v17, v141, s54, v17
	v_add_u32_e32 v18, 0xf400, v191
	ds_write2_b32 v18, v16, v17 offset0:100 offset1:230
	s_waitcnt vmcnt(0)
	v_and_b32_e32 v16, 63, v251
	v_lshrrev_b32_e32 v17, 3, v16
	v_mul_u32_u24_e32 v17, 0x90, v17
	v_and_b32_e32 v18, 7, v16
	v_lshl_add_u32 v17, v18, 4, v17
	v_mul_u32_u24_e32 v18, 0x1200, v254
	v_add_u32_e32 v18, 0x12000, v18
	v_add_u32_e32 v17, v17, v18
	v_and_b32_e32 v19, 31, v16
	v_mul_u32_u24_e32 v19, 0x90, v19
	v_lshrrev_b32_e32 v16, 5, v16
	v_lshl_add_u32 v19, v16, 4, v19
	v_add_u32_e32 v19, v19, v18
	ds_write_b128 v17, v[0:3]
	ds_write_b128 v17, v[4:7] offset:1152
	ds_write_b128 v17, v[8:11] offset:2304
	ds_write_b128 v17, v[12:15] offset:3456
	ds_read_b128 v[0:3], v19
	ds_read_b128 v[8:11], v19 offset:32
	ds_read_b128 v[4:7], v19 offset:64
	ds_read_b128 v[12:15], v19 offset:96
	ds_write_b128 v17, v[100:103]
	ds_write_b128 v17, v[104:107] offset:1152
	ds_write_b128 v17, v[108:111] offset:2304
	ds_write_b128 v17, v[112:115] offset:3456
	ds_read_b128 v[100:103], v19
	ds_read_b128 v[108:111], v19 offset:32
	ds_read_b128 v[104:107], v19 offset:64
	ds_read_b128 v[112:115], v19 offset:96
	s_waitcnt lgkmcnt(0)
	s_cbranch_vccnz .LBB0_354
	s_add_i32 s64, s1, s96
	s_and_b32 s64, s64, 0x780
	s_addk_i32 s64, 0xff80
	v_mov_b32_e32 v96, v97
	v_add_u32_e32 v16, s64, v182
	v_mov_b32_e32 v98, v97
	v_mov_b32_e32 v99, v97
	v_mov_b64_e32 v[80:81], v[96:97]
	v_mov_b64_e32 v[84:85], v[96:97]
	v_mov_b64_e32 v[92:93], v[96:97]
	v_mov_b64_e32 v[88:89], v[96:97]
	s_ashr_i32 s55, s33, 6
	s_and_b32 s69, s33, 3
	v_cmp_lt_i32_e32 vcc, -1, v16
	v_mov_b64_e32 v[82:83], v[98:99]
	v_mov_b64_e32 v[86:87], v[98:99]
	v_mov_b64_e32 v[94:95], v[98:99]
	v_mov_b64_e32 v[90:91], v[98:99]
	s_and_saveexec_b64 s[78:79], vcc
	s_cbranch_execz .LBB0_351
	v_readlane_b32 vcc_lo, v255, 6
	v_readlane_b32 vcc_hi, v255, 7
	v_add_u32_e32 v18, s64, v250
	v_lshl_add_u32 v18, s55, 11, v18
	s_lshl_b32 s94, s69, 7
	v_mov_b64_e32 v[16:17], vcc
	v_mad_i64_i32 v[16:17], vcc, v18, s65, v[16:17]
	v_lshl_add_u64 v[16:17], v[16:17], 0, s[94:95]
	v_mov_b32_e32 v153, v97
	v_lshl_add_u64 v[16:17], v[16:17], 0, v[248:249]
	s_movk_i32 s94, 0x6000
	global_load_dwordx4 v[80:83], v[16:17], off offset:2048
	v_lshl_add_u64 v[16:17], v[16:17], 0, s[94:95]
	global_load_dwordx4 v[84:87], v[16:17], off offset:2048
	v_lshl_add_u64 v[16:17], v[16:17], 0, s[94:95]
	global_load_dwordx4 v[88:91], v[16:17], off offset:2048
	v_lshl_add_u64 v[16:17], v[16:17], 0, s[94:95]
	global_load_dwordx4 v[92:95], v[16:17], off offset:2048
